# v22biashoist
# baseline (speedup 1.0000x reference)
; #define SBAR() __builtin_amdgcn_sched_barrier(0)
; #define PV_RD(F_, d0) do { constexpr int b_ = V_OFF + v_rd_off(d0, 0, 0); \
;         TRRD(F_[0], b_); TRRD(F_[1], b_ + 2048); TRRD(F_[2], b_ + 4096); TRRD(F_[3], b_ + 6144); TRRD(F_[4], b_ + 8192); TRRD(F_[5], b_ + 10240); TRRD(F_[6], b_ + 12288); TRRD(F_[7], b_ + 14336); } while (0)
; template <int k> __device__ __forceinline__ void par_snip(f32x16& p0, f32x16& p1, float& m_reg, float& pmax, float& alpha, float& mnL, float msk) {
;     constexpr float C2 = 1.4426950408889634f * SCALE;
;     if constexpr (k < 4) { constexpr int j = 4 * k; const float a = fmaxf(fmaxf(p0[j], p0[j + 1]), fmaxf(p0[j + 2], p0[j + 3])), b = fmaxf(fmaxf(p1[j], p1[j + 1]), fmaxf(p1[j + 2], p1[j + 3]));
;         pmax = (k == 0) ? fmaxf(a, b) : fmaxf(pmax, fmaxf(a, b)); }
;     else if constexpr (k == 4) { pmax += msk;
;         { auto rr = __builtin_amdgcn_permlane32_swap(__float_as_uint(pmax), __float_as_uint(pmax), false, false); pmax = fmaxf(__uint_as_float(rr[0]), __uint_as_float(rr[1])); }
;         const bool defer = __all((pmax - m_reg) * SCALE <= THR);
;         const float mn = defer ? m_reg : fmaxf(m_reg, pmax);
;         alpha = __builtin_amdgcn_exp2f((m_reg - mn) * C2); m_reg = mn; mnL = fmaf(-mn, C2, msk); }
;     else if constexpr (k < 9) { constexpr int j = 4 * (k - 5);
; #pragma unroll
;         for (int e = 0; e < 4; ++e) { p0[j + e] = fmaf(p0[j + e], C2, mnL); p1[j + e] = fmaf(p1[j + e], C2, mnL); } }
;     else if constexpr (k < 15) { constexpr int j = 2 * (k - 9); p0[j] = __builtin_amdgcn_exp2f(p0[j]); p0[j + 1] = __builtin_amdgcn_exp2f(p0[j + 1]); }
;     else if constexpr (k == 15) {
; #pragma unroll
;         for (int e = 12; e < 16; ++e) p0[e] = __builtin_amdgcn_exp2f(p0[e]); }
; __device__ __forceinline__ void stage_pv_par(f32x16* o, int vb0, bf16x8 pa0, bf16x8 pa1, bf16x8 pa2, bf16x8 pa3,
;                                              f32x16& x0, f32x16& x1, float& m_reg, float& alpha, float msk) {
;     ...
;     float pmax = 0.f, mnL = 0.f; s16x4 fA[8];
;     SBAR(); PV_RD(fA, 0); PV_WAIT(fA, 0); SBAR();
;     PVS(fA, 0); PV_RD(fA, 1); PV_WAIT(fA, 0); SBAR();
;     PVS(fA, 1); PV_RD(fA, 2); PV_WAIT(fA, 0); SBAR();
;     PVS(fA, 2); PV_RD(fA, 3); PV_WAIT(fA, 0); SBAR();
;     PVS(fA, 3);
.Lmy_mid_a:
	s_and_b32 s34, s85, 0xc000
	v_add_u32_e32 v217, s34, v225
	ds_read_b64_tr_b16 v[194:195], v217 offset:0
	ds_read_b64_tr_b16 v[196:197], v217 offset:0x800
	ds_read_b64_tr_b16 v[200:201], v217 offset:0x1000
	ds_read_b64_tr_b16 v[202:203], v217 offset:0x1800
	ds_read_b64_tr_b16 v[204:205], v217 offset:0x2000
	ds_read_b64_tr_b16 v[206:207], v217 offset:0x2800
	ds_read_b64_tr_b16 v[208:209], v217 offset:0x3000
	ds_read_b64_tr_b16 v[210:211], v217 offset:0x3800
	s_nop 0
	s_waitcnt lgkmcnt(0)
	s_nop 0
	v_mfma_f32_32x32x16_bf16 v[64:79], v[194:197], v[2:5], v[64:79]
	s_nop 5
	v_max3_f32 v0, v96, v97, v98
	v_max3_f32 v194, v112, v113, v114
	v_max3_f32 v0, v0, v99, v100
	v_max3_f32 v194, v194, v115, v116
	v_mfma_f32_32x32x16_bf16 v[64:79], v[200:203], v[6:9], v[64:79]
	v_max3_f32 v0, v0, v101, v102
	v_max3_f32 v194, v194, v117, v118
	v_max3_f32 v0, v0, v103, v104
	v_max3_f32 v194, v194, v119, v120
	v_mfma_f32_32x32x16_bf16 v[64:79], v[204:207], v[10:13], v[64:79]
	v_max3_f32 v0, v0, v105, v106
	v_max3_f32 v194, v194, v121, v122
	v_max3_f32 v0, v0, v107, v108
	v_max3_f32 v194, v194, v123, v124
	v_mfma_f32_32x32x16_bf16 v[64:79], v[208:211], v[176:179], v[64:79]
	v_max3_f32 v0, v0, v109, v110
	v_max3_f32 v194, v194, v125, v126
	v_max3_f32 v0, v0, v111, v127
	v_max_f32_e32 v0, v0, v194
	ds_read_b64_tr_b16 v[194:195], v217 offset:0x200
	ds_read_b64_tr_b16 v[196:197], v217 offset:0xa00
	ds_read_b64_tr_b16 v[200:201], v217 offset:0x1200
	ds_read_b64_tr_b16 v[202:203], v217 offset:0x1a00
	ds_read_b64_tr_b16 v[204:205], v217 offset:0x2200
	ds_read_b64_tr_b16 v[206:207], v217 offset:0x2a00
	ds_read_b64_tr_b16 v[208:209], v217 offset:0x3200
	ds_read_b64_tr_b16 v[210:211], v217 offset:0x3a00
	s_nop 0
	s_waitcnt lgkmcnt(0)
	v_add_f32_e32 v0, v216, v0
	v_mfma_f32_32x32x16_bf16 v[48:63], v[194:197], v[2:5], v[48:63]
	v_mov_b32_e32 v194, v0
	s_nop 1
	v_permlane32_swap_b32_e32 v0, v194
	v_max_f32_e32 v0, v0, v194
	v_sub_f32_e32 v194, v0, v244
	v_cmp_ge_f32_e32 vcc, 0x42ddb3d8, v194
	v_max_f32_e32 v0, v244, v0
	s_nop 0
	v_cndmask_b32_e32 v246, v0, v244, vcc
	v_fmac_f32_e32 v216, 0xbdd53b94, v246
	v_sub_f32_e32 v0, v244, v246
	v_mul_f32_e32 v0, 0x3dd53b94, v0
	v_exp_f32_e32 v0, v0
	v_mfma_f32_32x32x16_bf16 v[48:63], v[200:203], v[6:9], v[48:63]
	v_fmamk_f32 v96, v96, 0x3dd53b94, v216
	v_fmamk_f32 v97, v97, 0x3dd53b94, v216
	v_fmamk_f32 v98, v98, 0x3dd53b94, v216
	v_fmamk_f32 v99, v99, 0x3dd53b94, v216
	v_exp_f32_e32 v243, v96
	v_mfma_f32_32x32x16_bf16 v[48:63], v[204:207], v[10:13], v[48:63]
	v_fmamk_f32 v100, v100, 0x3dd53b94, v216
	v_fmamk_f32 v101, v101, 0x3dd53b94, v216
	v_exp_f32_e32 v242, v97
	v_exp_f32_e32 v241, v98
	v_mfma_f32_32x32x16_bf16 v[48:63], v[208:211], v[176:179], v[48:63]
	v_fmamk_f32 v102, v102, 0x3dd53b94, v216
	v_fmamk_f32 v103, v103, 0x3dd53b94, v216
	v_exp_f32_e32 v240, v99
	v_exp_f32_e32 v239, v100
	ds_read_b64_tr_b16 v[194:195], v217 offset:0x400
	ds_read_b64_tr_b16 v[196:197], v217 offset:0xc00
	ds_read_b64_tr_b16 v[200:201], v217 offset:0x1400
	ds_read_b64_tr_b16 v[202:203], v217 offset:0x1c00
	ds_read_b64_tr_b16 v[204:205], v217 offset:0x2400
	ds_read_b64_tr_b16 v[206:207], v217 offset:0x2c00
	ds_read_b64_tr_b16 v[208:209], v217 offset:0x3400
	ds_read_b64_tr_b16 v[210:211], v217 offset:0x3c00
	s_nop 0
	s_waitcnt lgkmcnt(0)
	s_nop 0
	v_mfma_f32_32x32x16_bf16 v[32:47], v[194:197], v[2:5], v[32:47]
	v_fmamk_f32 v104, v104, 0x3dd53b94, v216
	v_fmamk_f32 v105, v105, 0x3dd53b94, v216
	v_exp_f32_e32 v238, v101
	v_exp_f32_e32 v237, v102
	v_mfma_f32_32x32x16_bf16 v[32:47], v[200:203], v[6:9], v[32:47]
	v_fmamk_f32 v106, v106, 0x3dd53b94, v216
	v_fmamk_f32 v107, v107, 0x3dd53b94, v216
	v_exp_f32_e32 v236, v103
	v_exp_f32_e32 v235, v104
	v_mfma_f32_32x32x16_bf16 v[32:47], v[204:207], v[10:13], v[32:47]
	v_fmamk_f32 v108, v108, 0x3dd53b94, v216
	v_fmamk_f32 v109, v109, 0x3dd53b94, v216
	v_exp_f32_e32 v234, v105
	v_exp_f32_e32 v233, v106
	v_mfma_f32_32x32x16_bf16 v[32:47], v[208:211], v[176:179], v[32:47]
	v_fmamk_f32 v110, v110, 0x3dd53b94, v216
	v_fmamk_f32 v111, v111, 0x3dd53b94, v216
	v_exp_f32_e32 v232, v107
	v_exp_f32_e32 v231, v108
	ds_read_b64_tr_b16 v[194:195], v217 offset:0x600
	ds_read_b64_tr_b16 v[196:197], v217 offset:0xe00
	ds_read_b64_tr_b16 v[200:201], v217 offset:0x1600
	ds_read_b64_tr_b16 v[202:203], v217 offset:0x1e00
	ds_read_b64_tr_b16 v[204:205], v217 offset:0x2600
	ds_read_b64_tr_b16 v[206:207], v217 offset:0x2e00
	ds_read_b64_tr_b16 v[208:209], v217 offset:0x3600
	ds_read_b64_tr_b16 v[210:211], v217 offset:0x3e00
	s_nop 0
	s_waitcnt lgkmcnt(0)
	s_nop 0
	v_mfma_f32_32x32x16_bf16 v[16:31], v[194:197], v[2:5], v[16:31]
	v_exp_f32_e32 v230, v109
	v_fmamk_f32 v14, v112, 0x3dd53b94, v216
	v_fmamk_f32 v15, v113, 0x3dd53b94, v216
	v_fmamk_f32 v116, v116, 0x3dd53b94, v216
	v_fmamk_f32 v117, v117, 0x3dd53b94, v216
	v_mfma_f32_32x32x16_bf16 v[16:31], v[200:203], v[6:9], v[16:31]
	v_fmamk_f32 v118, v118, 0x3dd53b94, v216
	v_fmamk_f32 v119, v119, 0x3dd53b94, v216
	v_fmamk_f32 v120, v120, 0x3dd53b94, v216
	v_fmamk_f32 v121, v121, 0x3dd53b94, v216
	v_fmamk_f32 v122, v122, 0x3dd53b94, v216
	v_fmamk_f32 v123, v123, 0x3dd53b94, v216
	v_mfma_f32_32x32x16_bf16 v[16:31], v[204:207], v[10:13], v[16:31]
	v_fmamk_f32 v124, v124, 0x3dd53b94, v216
	v_fmamk_f32 v125, v125, 0x3dd53b94, v216
	v_fmamk_f32 v126, v126, 0x3dd53b94, v216
	v_fmamk_f32 v127, v127, 0x3dd53b94, v216
	v_mfma_f32_32x32x16_bf16 v[16:31], v[208:211], v[176:179], v[16:31]
	v_cmp_gt_f32_e32 vcc, 1.0, v0
	s_cbranch_vccz .LBB0_330
	v_pk_mul_f32 v[78:79], v[78:79], v[0:1] op_sel_hi:[1,0]
	v_pk_mul_f32 v[76:77], v[76:77], v[0:1] op_sel_hi:[1,0]
	v_pk_mul_f32 v[74:75], v[74:75], v[0:1] op_sel_hi:[1,0]
	v_pk_mul_f32 v[72:73], v[72:73], v[0:1] op_sel_hi:[1,0]
	v_pk_mul_f32 v[70:71], v[70:71], v[0:1] op_sel_hi:[1,0]
	v_pk_mul_f32 v[68:69], v[68:69], v[0:1] op_sel_hi:[1,0]
	v_pk_mul_f32 v[66:67], v[66:67], v[0:1] op_sel_hi:[1,0]
	v_pk_mul_f32 v[64:65], v[64:65], v[0:1] op_sel_hi:[1,0]
	v_pk_mul_f32 v[62:63], v[0:1], v[62:63] op_sel_hi:[0,1]
	v_pk_mul_f32 v[60:61], v[0:1], v[60:61] op_sel_hi:[0,1]
	v_pk_mul_f32 v[58:59], v[0:1], v[58:59] op_sel_hi:[0,1]
	v_pk_mul_f32 v[56:57], v[0:1], v[56:57] op_sel_hi:[0,1]
	v_pk_mul_f32 v[54:55], v[0:1], v[54:55] op_sel_hi:[0,1]
	v_pk_mul_f32 v[52:53], v[0:1], v[52:53] op_sel_hi:[0,1]
	v_pk_mul_f32 v[50:51], v[0:1], v[50:51] op_sel_hi:[0,1]
	v_pk_mul_f32 v[48:49], v[0:1], v[48:49] op_sel_hi:[0,1]
	v_pk_mul_f32 v[46:47], v[0:1], v[46:47] op_sel_hi:[0,1]
	v_pk_mul_f32 v[44:45], v[0:1], v[44:45] op_sel_hi:[0,1]
	v_pk_mul_f32 v[42:43], v[0:1], v[42:43] op_sel_hi:[0,1]
	v_pk_mul_f32 v[40:41], v[0:1], v[40:41] op_sel_hi:[0,1]
	v_pk_mul_f32 v[38:39], v[0:1], v[38:39] op_sel_hi:[0,1]
	v_pk_mul_f32 v[36:37], v[0:1], v[36:37] op_sel_hi:[0,1]
	v_pk_mul_f32 v[34:35], v[0:1], v[34:35] op_sel_hi:[0,1]
	v_pk_mul_f32 v[32:33], v[0:1], v[32:33] op_sel_hi:[0,1]
	v_pk_mul_f32 v[30:31], v[0:1], v[30:31] op_sel_hi:[0,1]
	v_pk_mul_f32 v[28:29], v[0:1], v[28:29] op_sel_hi:[0,1]
	v_pk_mul_f32 v[26:27], v[0:1], v[26:27] op_sel_hi:[0,1]
	v_pk_mul_f32 v[24:25], v[0:1], v[24:25] op_sel_hi:[0,1]
	v_pk_mul_f32 v[22:23], v[0:1], v[22:23] op_sel_hi:[0,1]
	v_pk_mul_f32 v[20:21], v[0:1], v[20:21] op_sel_hi:[0,1]
	v_pk_mul_f32 v[18:19], v[0:1], v[18:19] op_sel_hi:[0,1]
	v_pk_mul_f32 v[16:17], v[0:1], v[16:17] op_sel_hi:[0,1]

; #define SBAR() __builtin_amdgcn_sched_barrier(0)
; #define PV_RD(F_, d0) do { constexpr int b_ = V_OFF + v_rd_off(d0, 0, 0); \
;         TRRD(F_[0], b_); TRRD(F_[1], b_ + 2048); TRRD(F_[2], b_ + 4096); TRRD(F_[3], b_ + 6144); TRRD(F_[4], b_ + 8192); TRRD(F_[5], b_ + 10240); TRRD(F_[6], b_ + 12288); TRRD(F_[7], b_ + 14336); } while (0)
; template <int k> __device__ __forceinline__ void par_snip(f32x16& p0, f32x16& p1, float& m_reg, float& pmax, float& alpha, float& mnL, float msk) {
;     constexpr float C2 = 1.4426950408889634f * SCALE;
;     if constexpr (k < 4) { constexpr int j = 4 * k; const float a = fmaxf(fmaxf(p0[j], p0[j + 1]), fmaxf(p0[j + 2], p0[j + 3])), b = fmaxf(fmaxf(p1[j], p1[j + 1]), fmaxf(p1[j + 2], p1[j + 3]));
;         pmax = (k == 0) ? fmaxf(a, b) : fmaxf(pmax, fmaxf(a, b)); }
;     else if constexpr (k == 4) { pmax += msk;
;         { auto rr = __builtin_amdgcn_permlane32_swap(__float_as_uint(pmax), __float_as_uint(pmax), false, false); pmax = fmaxf(__uint_as_float(rr[0]), __uint_as_float(rr[1])); }
;         const bool defer = __all((pmax - m_reg) * SCALE <= THR);
;         const float mn = defer ? m_reg : fmaxf(m_reg, pmax);
;         alpha = __builtin_amdgcn_exp2f((m_reg - mn) * C2); m_reg = mn; mnL = fmaf(-mn, C2, msk); }
;     else if constexpr (k < 9) { constexpr int j = 4 * (k - 5);
; #pragma unroll
;         for (int e = 0; e < 4; ++e) { p0[j + e] = fmaf(p0[j + e], C2, mnL); p1[j + e] = fmaf(p1[j + e], C2, mnL); } }
;     else if constexpr (k < 15) { constexpr int j = 2 * (k - 9); p0[j] = __builtin_amdgcn_exp2f(p0[j]); p0[j + 1] = __builtin_amdgcn_exp2f(p0[j + 1]); }
;     else if constexpr (k == 15) {
; #pragma unroll
;         for (int e = 12; e < 16; ++e) p0[e] = __builtin_amdgcn_exp2f(p0[e]); }
; __device__ __forceinline__ void stage_pv_par(f32x16* o, int vb0, bf16x8 pa0, bf16x8 pa1, bf16x8 pa2, bf16x8 pa3,
;                                              f32x16& x0, f32x16& x1, float& m_reg, float& alpha, float msk) {
;     ...
;     float pmax = 0.f, mnL = 0.f; s16x4 fA[8];
;     SBAR(); PV_RD(fA, 0); PV_WAIT(fA, 0); SBAR();
;     PVS(fA, 0); PV_RD(fA, 1); PV_WAIT(fA, 0); SBAR();
;     PVS(fA, 1); PV_RD(fA, 2); PV_WAIT(fA, 0); SBAR();
;     PVS(fA, 2); PV_RD(fA, 3); PV_WAIT(fA, 0); SBAR();
;     PVS(fA, 3);
.Lmy_mid_b:
	s_and_b32 s34, s34, 0xc000
	v_add_u32_e32 v217, s34, v225
	ds_read_b64_tr_b16 v[194:195], v217 offset:0
	ds_read_b64_tr_b16 v[196:197], v217 offset:0x800
	ds_read_b64_tr_b16 v[232:233], v217 offset:0x1000
	ds_read_b64_tr_b16 v[234:235], v217 offset:0x1800
	ds_read_b64_tr_b16 v[236:237], v217 offset:0x2000
	ds_read_b64_tr_b16 v[238:239], v217 offset:0x2800
	ds_read_b64_tr_b16 v[240:241], v217 offset:0x3000
	ds_read_b64_tr_b16 v[242:243], v217 offset:0x3800
	s_nop 0
	s_waitcnt lgkmcnt(0)
	s_nop 0
	v_mfma_f32_32x32x16_bf16 v[64:79], v[194:197], v[2:5], v[64:79]
	s_nop 5
	v_max3_f32 v192, v96, v97, v98
	v_max3_f32 v194, v80, v81, v82
	v_max3_f32 v192, v192, v99, v100
	v_max3_f32 v194, v194, v83, v84
	v_mfma_f32_32x32x16_bf16 v[64:79], v[232:235], v[6:9], v[64:79]
	v_max3_f32 v192, v192, v101, v102
	v_max3_f32 v194, v194, v85, v86
	v_max3_f32 v192, v192, v103, v104
	v_max3_f32 v194, v194, v87, v88
	v_mfma_f32_32x32x16_bf16 v[64:79], v[236:239], v[10:13], v[64:79]
	v_max3_f32 v192, v192, v105, v106
	v_max3_f32 v194, v194, v89, v90
	v_max3_f32 v192, v192, v107, v108
	v_max3_f32 v194, v194, v91, v92
	v_mfma_f32_32x32x16_bf16 v[64:79], v[240:243], v[112:115], v[64:79]
	v_max3_f32 v192, v192, v109, v110
	v_max3_f32 v194, v194, v93, v94
	v_max3_f32 v192, v192, v111, v95
	v_max_f32_e32 v192, v192, v194
	ds_read_b64_tr_b16 v[194:195], v217 offset:0x200
	ds_read_b64_tr_b16 v[196:197], v217 offset:0xa00
	ds_read_b64_tr_b16 v[232:233], v217 offset:0x1200
	ds_read_b64_tr_b16 v[234:235], v217 offset:0x1a00
	ds_read_b64_tr_b16 v[236:237], v217 offset:0x2200
	ds_read_b64_tr_b16 v[238:239], v217 offset:0x2a00
	ds_read_b64_tr_b16 v[240:241], v217 offset:0x3200
	ds_read_b64_tr_b16 v[242:243], v217 offset:0x3a00
	s_nop 0
	s_waitcnt lgkmcnt(0)
	v_add_f32_e32 v192, v178, v192
	v_mfma_f32_32x32x16_bf16 v[48:63], v[194:197], v[2:5], v[48:63]
	v_mov_b32_e32 v194, v192
	s_nop 1
	v_permlane32_swap_b32_e32 v192, v194
	v_max_f32_e32 v192, v192, v194
	v_sub_f32_e32 v194, v192, v246
	v_cmp_ge_f32_e32 vcc, 0x42ddb3d8, v194
	v_max_f32_e32 v192, v246, v192
	s_nop 0
	v_cndmask_b32_e32 v244, v192, v246, vcc
	v_fmac_f32_e32 v178, 0xbdd53b94, v244
	v_sub_f32_e32 v192, v246, v244
	v_mul_f32_e32 v192, 0x3dd53b94, v192
	v_exp_f32_e32 v192, v192
	v_mfma_f32_32x32x16_bf16 v[48:63], v[232:235], v[6:9], v[48:63]
	v_fmamk_f32 v214, v80, 0x3dd53b94, v178
	v_fmamk_f32 v215, v81, 0x3dd53b94, v178
	v_fmamk_f32 v212, v82, 0x3dd53b94, v178
	v_fmamk_f32 v213, v83, 0x3dd53b94, v178
	v_fmamk_f32 v210, v84, 0x3dd53b94, v178
	v_fmamk_f32 v211, v85, 0x3dd53b94, v178
	v_mfma_f32_32x32x16_bf16 v[48:63], v[236:239], v[10:13], v[48:63]
	v_fmamk_f32 v208, v86, 0x3dd53b94, v178
	v_fmamk_f32 v209, v87, 0x3dd53b94, v178
	v_fmamk_f32 v206, v88, 0x3dd53b94, v178
	v_fmamk_f32 v207, v89, 0x3dd53b94, v178
	v_fmamk_f32 v204, v90, 0x3dd53b94, v178
	v_fmamk_f32 v205, v91, 0x3dd53b94, v178
	v_mfma_f32_32x32x16_bf16 v[48:63], v[240:243], v[112:115], v[48:63]
	v_fmamk_f32 v202, v92, 0x3dd53b94, v178
	v_fmamk_f32 v203, v93, 0x3dd53b94, v178
	v_fmamk_f32 v200, v94, 0x3dd53b94, v178
	v_fmamk_f32 v201, v95, 0x3dd53b94, v178
	v_fmamk_f32 v96, v96, 0x3dd53b94, v178
	v_fmamk_f32 v97, v97, 0x3dd53b94, v178
	ds_read_b64_tr_b16 v[194:195], v217 offset:0x400
	ds_read_b64_tr_b16 v[196:197], v217 offset:0xc00
	ds_read_b64_tr_b16 v[232:233], v217 offset:0x1400
	ds_read_b64_tr_b16 v[234:235], v217 offset:0x1c00
	ds_read_b64_tr_b16 v[236:237], v217 offset:0x2400
	ds_read_b64_tr_b16 v[238:239], v217 offset:0x2c00
	ds_read_b64_tr_b16 v[240:241], v217 offset:0x3400
	ds_read_b64_tr_b16 v[242:243], v217 offset:0x3c00
	s_nop 0
	s_waitcnt lgkmcnt(0)
	s_nop 0
	v_mfma_f32_32x32x16_bf16 v[32:47], v[194:197], v[2:5], v[32:47]
	v_fmamk_f32 v98, v98, 0x3dd53b94, v178
	v_fmamk_f32 v99, v99, 0x3dd53b94, v178
	v_exp_f32_e32 v80, v96
	v_exp_f32_e32 v81, v97
	v_mfma_f32_32x32x16_bf16 v[32:47], v[232:235], v[6:9], v[32:47]
	v_fmamk_f32 v100, v100, 0x3dd53b94, v178
	v_fmamk_f32 v101, v101, 0x3dd53b94, v178
	v_exp_f32_e32 v82, v98
	v_exp_f32_e32 v83, v99
	v_mfma_f32_32x32x16_bf16 v[32:47], v[236:239], v[10:13], v[32:47]
	v_fmamk_f32 v102, v102, 0x3dd53b94, v178
	v_fmamk_f32 v103, v103, 0x3dd53b94, v178
	v_exp_f32_e32 v84, v100
	v_exp_f32_e32 v85, v101
	v_mfma_f32_32x32x16_bf16 v[32:47], v[240:243], v[112:115], v[32:47]
	v_fmamk_f32 v104, v104, 0x3dd53b94, v178
	v_fmamk_f32 v105, v105, 0x3dd53b94, v178
	v_exp_f32_e32 v86, v102
	v_exp_f32_e32 v87, v103
	ds_read_b64_tr_b16 v[194:195], v217 offset:0x600
	ds_read_b64_tr_b16 v[196:197], v217 offset:0xe00
	ds_read_b64_tr_b16 v[232:233], v217 offset:0x1600
	ds_read_b64_tr_b16 v[234:235], v217 offset:0x1e00
	ds_read_b64_tr_b16 v[236:237], v217 offset:0x2600
	ds_read_b64_tr_b16 v[238:239], v217 offset:0x2e00
	ds_read_b64_tr_b16 v[240:241], v217 offset:0x3600
	ds_read_b64_tr_b16 v[242:243], v217 offset:0x3e00
	s_nop 0
	s_waitcnt lgkmcnt(0)
	s_nop 0
	v_mfma_f32_32x32x16_bf16 v[16:31], v[194:197], v[2:5], v[16:31]
	v_fmamk_f32 v106, v106, 0x3dd53b94, v178
	v_fmamk_f32 v107, v107, 0x3dd53b94, v178
	v_exp_f32_e32 v88, v104
	v_exp_f32_e32 v89, v105
	v_mfma_f32_32x32x16_bf16 v[16:31], v[232:235], v[6:9], v[16:31]
	v_fmamk_f32 v108, v108, 0x3dd53b94, v178
	v_fmamk_f32 v109, v109, 0x3dd53b94, v178
	v_exp_f32_e32 v90, v106
	v_exp_f32_e32 v91, v107
	v_mfma_f32_32x32x16_bf16 v[16:31], v[236:239], v[10:13], v[16:31]
	v_fmamk_f32 v110, v110, 0x3dd53b94, v178
	v_fmamk_f32 v111, v111, 0x3dd53b94, v178
	v_exp_f32_e32 v92, v108
	v_exp_f32_e32 v93, v109
	v_mfma_f32_32x32x16_bf16 v[16:31], v[240:243], v[112:115], v[16:31]
	v_cmp_gt_f32_e32 vcc, 1.0, v192
	s_cbranch_vccz .LBB0_335
	v_pk_mul_f32 v[78:79], v[78:79], v[192:193] op_sel_hi:[1,0]
	v_pk_mul_f32 v[76:77], v[76:77], v[192:193] op_sel_hi:[1,0]
	v_pk_mul_f32 v[74:75], v[74:75], v[192:193] op_sel_hi:[1,0]
	v_pk_mul_f32 v[72:73], v[72:73], v[192:193] op_sel_hi:[1,0]
	v_pk_mul_f32 v[70:71], v[70:71], v[192:193] op_sel_hi:[1,0]
	v_pk_mul_f32 v[68:69], v[68:69], v[192:193] op_sel_hi:[1,0]
	v_pk_mul_f32 v[66:67], v[66:67], v[192:193] op_sel_hi:[1,0]
	v_pk_mul_f32 v[64:65], v[64:65], v[192:193] op_sel_hi:[1,0]
	v_pk_mul_f32 v[62:63], v[192:193], v[62:63] op_sel_hi:[0,1]
	v_pk_mul_f32 v[60:61], v[192:193], v[60:61] op_sel_hi:[0,1]
	v_pk_mul_f32 v[58:59], v[192:193], v[58:59] op_sel_hi:[0,1]
	v_pk_mul_f32 v[56:57], v[192:193], v[56:57] op_sel_hi:[0,1]
	v_pk_mul_f32 v[54:55], v[192:193], v[54:55] op_sel_hi:[0,1]
	v_pk_mul_f32 v[52:53], v[192:193], v[52:53] op_sel_hi:[0,1]
	v_pk_mul_f32 v[50:51], v[192:193], v[50:51] op_sel_hi:[0,1]
	v_pk_mul_f32 v[48:49], v[192:193], v[48:49] op_sel_hi:[0,1]
	v_pk_mul_f32 v[46:47], v[192:193], v[46:47] op_sel_hi:[0,1]
	v_pk_mul_f32 v[44:45], v[192:193], v[44:45] op_sel_hi:[0,1]
	v_pk_mul_f32 v[42:43], v[192:193], v[42:43] op_sel_hi:[0,1]
	v_pk_mul_f32 v[40:41], v[192:193], v[40:41] op_sel_hi:[0,1]
	v_pk_mul_f32 v[38:39], v[192:193], v[38:39] op_sel_hi:[0,1]
	v_pk_mul_f32 v[36:37], v[192:193], v[36:37] op_sel_hi:[0,1]
	v_pk_mul_f32 v[34:35], v[192:193], v[34:35] op_sel_hi:[0,1]
	v_pk_mul_f32 v[32:33], v[192:193], v[32:33] op_sel_hi:[0,1]
	v_pk_mul_f32 v[30:31], v[192:193], v[30:31] op_sel_hi:[0,1]
	v_pk_mul_f32 v[28:29], v[192:193], v[28:29] op_sel_hi:[0,1]
	v_pk_mul_f32 v[26:27], v[192:193], v[26:27] op_sel_hi:[0,1]
	v_pk_mul_f32 v[24:25], v[192:193], v[24:25] op_sel_hi:[0,1]
	v_pk_mul_f32 v[22:23], v[192:193], v[22:23] op_sel_hi:[0,1]
	v_pk_mul_f32 v[20:21], v[192:193], v[20:21] op_sel_hi:[0,1]
	v_pk_mul_f32 v[18:19], v[192:193], v[18:19] op_sel_hi:[0,1]
	v_pk_mul_f32 v[16:17], v[192:193], v[16:17] op_sel_hi:[0,1]
